# norm phases: the 22 remaining gain/scale/shift vector loads of a chunk also issued up front into a scratch quad (L1 prefetch) so the 8 waited load groups hit the L1; on top of v_micro5
# speedup vs baseline: 1.0090x; 1.0079x over previous
.LBB0_269:
	v_lshlrev_b32_e32 v4, 3, v130
	v_add_u32_e32 v5, 0xffffe000, v4
	s_movk_i32 s4, 0x3ff
	v_ashrrev_i32_e32 v5, 10, v5
	v_cmp_lt_i32_e32 vcc, s4, v130
	v_readlane_b32 s4, v255, 24
	s_mov_b32 s18, 0
	v_cndmask_b32_e32 v5, 8, v5, vcc
	v_add_u32_e32 v5, s4, v5
	v_mul_hi_i32_i24_e32 v7, 0x12000, v5
	v_mul_i32_i24_e32 v6, 0x12000, v5
	v_lshl_add_u64 v[32:33], s[10:11], 0, v[6:7]
	s_mov_b64 s[4:5], 0x2000
	v_ashrrev_i32_e32 v5, 31, v4
	v_lshl_add_u64 v[34:35], v[32:33], 0, s[4:5]
	v_lshlrev_b64 v[4:5], 12, v[4:5]
	v_lshl_add_u64 v[4:5], v[36:37], 0, v[4:5]
	v_lshl_add_u64 v[8:9], v[34:35], 0, v[2:3]
	global_load_dwordx2 v[126:127], v[4:5], off
	global_load_dwordx2 v[124:125], v[4:5], off offset:512
	global_load_dwordx2 v[122:123], v[4:5], off offset:1024
	global_load_dwordx2 v[120:121], v[4:5], off offset:1536
	global_load_dwordx2 v[118:119], v[4:5], off offset:2048
	global_load_dwordx2 v[116:117], v[4:5], off offset:2560
	global_load_dwordx2 v[110:111], v[4:5], off offset:3072
	global_load_dwordx2 v[108:109], v[4:5], off offset:3584
	s_nop 0
	global_load_dwordx4 v[4:7], v[38:39], off
	v_lshl_add_u64 v[24:25], v[32:33], 0, v[2:3]
	global_load_dwordx4 v[8:11], v[8:9], off
	v_lshl_add_u64 v[12:13], v[34:35], 0, v[50:51]
	v_lshl_add_u64 v[16:17], v[34:35], 0, v[52:53]
	v_lshl_add_u64 v[20:21], v[34:35], 0, v[54:55]
	v_lshl_add_u64 v[28:29], v[34:35], 0, v[58:59]
	v_lshl_add_u64 v[104:105], v[34:35], 0, v[62:63]
	global_load_dwordx4 v[244:247], v[24:25], off
	global_load_dwordx4 v[244:247], v[38:39], off offset:1024
	global_load_dwordx4 v[244:247], v[12:13], off
	global_load_dwordx4 v[244:247], v[24:25], off offset:1024
	global_load_dwordx4 v[244:247], v[38:39], off offset:2048
	global_load_dwordx4 v[244:247], v[16:17], off
	global_load_dwordx4 v[244:247], v[24:25], off offset:2048
	global_load_dwordx4 v[244:247], v[38:39], off offset:3072
	global_load_dwordx4 v[244:247], v[20:21], off
	global_load_dwordx4 v[244:247], v[24:25], off offset:3072
	global_load_dwordx4 v[244:247], v[40:41], off
	v_lshl_add_u64 v[250:251], v[34:35], 0, v[56:57]
	global_load_dwordx4 v[244:247], v[250:251], off
	v_lshl_add_u64 v[250:251], v[32:33], 0, v[56:57]
	global_load_dwordx4 v[244:247], v[250:251], off
	global_load_dwordx4 v[244:247], v[42:43], off
	global_load_dwordx4 v[244:247], v[28:29], off
	v_lshl_add_u64 v[250:251], v[32:33], 0, v[58:59]
	global_load_dwordx4 v[244:247], v[250:251], off
	global_load_dwordx4 v[244:247], v[44:45], off
	global_load_dwordx4 v[244:247], v[104:105], off
	v_lshl_add_u64 v[250:251], v[32:33], 0, v[62:63]
	global_load_dwordx4 v[244:247], v[250:251], off
	global_load_dwordx4 v[244:247], v[46:47], off
	v_lshl_add_u64 v[250:251], v[34:35], 0, v[64:65]
	global_load_dwordx4 v[244:247], v[250:251], off
	v_lshl_add_u64 v[250:251], v[32:33], 0, v[64:65]
	global_load_dwordx4 v[244:247], v[250:251], off
	s_waitcnt vmcnt(0)
	v_pk_add_f32 v[10:11], v[10:11], 1.0 op_sel_hi:[1,0]
	v_pk_add_f32 v[8:9], v[8:9], 1.0 op_sel_hi:[1,0]
	v_pk_mul_f32 v[80:81], v[6:7], v[10:11]
	v_pk_mul_f32 v[82:83], v[4:5], v[8:9]
	global_load_dwordx4 v[4:7], v[24:25], off
	global_load_dwordx4 v[8:11], v[38:39], off offset:1024
	s_nop 0
	global_load_dwordx4 v[12:15], v[12:13], off
	s_waitcnt vmcnt(0)
	v_pk_add_f32 v[14:15], v[14:15], 1.0 op_sel_hi:[1,0]
	v_pk_add_f32 v[12:13], v[12:13], 1.0 op_sel_hi:[1,0]
	v_pk_mul_f32 v[84:85], v[10:11], v[14:15]
	v_pk_mul_f32 v[86:87], v[8:9], v[12:13]
	global_load_dwordx4 v[8:11], v[24:25], off offset:1024
	global_load_dwordx4 v[12:15], v[38:39], off offset:2048
	s_nop 0
	global_load_dwordx4 v[16:19], v[16:17], off
	s_waitcnt vmcnt(0)
	v_pk_add_f32 v[18:19], v[18:19], 1.0 op_sel_hi:[1,0]
	v_pk_add_f32 v[16:17], v[16:17], 1.0 op_sel_hi:[1,0]
	v_pk_mul_f32 v[88:89], v[14:15], v[18:19]
	v_pk_mul_f32 v[90:91], v[12:13], v[16:17]
	global_load_dwordx4 v[12:15], v[24:25], off offset:2048
	global_load_dwordx4 v[16:19], v[38:39], off offset:3072
	s_nop 0
	global_load_dwordx4 v[20:23], v[20:21], off
	s_waitcnt vmcnt(0)
	v_pk_add_f32 v[22:23], v[22:23], 1.0 op_sel_hi:[1,0]
	v_pk_add_f32 v[20:21], v[20:21], 1.0 op_sel_hi:[1,0]
	v_pk_mul_f32 v[92:93], v[18:19], v[22:23]
	v_pk_mul_f32 v[94:95], v[16:17], v[20:21]
	global_load_dwordx4 v[16:19], v[24:25], off offset:3072
	global_load_dwordx4 v[20:23], v[40:41], off
	v_lshl_add_u64 v[24:25], v[34:35], 0, v[56:57]
	global_load_dwordx4 v[24:27], v[24:25], off
	v_lshl_add_u64 v[34:35], v[34:35], 0, v[64:65]
	s_waitcnt vmcnt(0)
	v_pk_add_f32 v[24:25], v[24:25], 1.0 op_sel_hi:[1,0]
	v_pk_add_f32 v[26:27], v[26:27], 1.0 op_sel_hi:[1,0]
	v_pk_mul_f32 v[98:99], v[20:21], v[24:25]
	v_lshl_add_u64 v[20:21], v[32:33], 0, v[56:57]
	v_pk_mul_f32 v[96:97], v[22:23], v[26:27]
	global_load_dwordx4 v[20:23], v[20:21], off
	s_nop 0
	global_load_dwordx4 v[24:27], v[42:43], off
	s_nop 0
	global_load_dwordx4 v[28:31], v[28:29], off
	s_waitcnt vmcnt(0)
	v_pk_add_f32 v[28:29], v[28:29], 1.0 op_sel_hi:[1,0]
	v_pk_add_f32 v[30:31], v[30:31], 1.0 op_sel_hi:[1,0]
	v_pk_mul_f32 v[102:103], v[24:25], v[28:29]
	v_lshl_add_u64 v[24:25], v[32:33], 0, v[58:59]
	v_pk_mul_f32 v[100:101], v[26:27], v[30:31]
	global_load_dwordx4 v[24:27], v[24:25], off
	s_nop 0
	global_load_dwordx4 v[28:31], v[44:45], off
	s_nop 0
	global_load_dwordx4 v[104:107], v[104:105], off
	s_waitcnt vmcnt(0)
	v_pk_add_f32 v[106:107], v[106:107], 1.0 op_sel_hi:[1,0]
	v_pk_add_f32 v[112:113], v[104:105], 1.0 op_sel_hi:[1,0]
	v_pk_mul_f32 v[104:105], v[30:31], v[106:107]
	v_pk_mul_f32 v[106:107], v[28:29], v[112:113]
	v_lshl_add_u64 v[28:29], v[32:33], 0, v[62:63]
	global_load_dwordx4 v[28:31], v[28:29], off
	s_nop 0
	global_load_dwordx4 v[132:135], v[46:47], off
	global_load_dwordx4 v[112:115], v[34:35], off
	v_lshl_add_u64 v[32:33], v[32:33], 0, v[64:65]
	s_waitcnt vmcnt(0)
	v_pk_add_f32 v[34:35], v[114:115], 1.0 op_sel_hi:[1,0]
	v_pk_add_f32 v[114:115], v[112:113], 1.0 op_sel_hi:[1,0]
	v_pk_mul_f32 v[112:113], v[134:135], v[34:35]
	global_load_dwordx4 v[32:35], v[32:33], off
	v_pk_mul_f32 v[114:115], v[132:133], v[114:115]
	s_cmp_eq_u32 s18, 7
	v_add_u32_e32 v128, s18, v131
	s_cbranch_scc1 .LBB0_272
	s_branch .LBB0_271

.LBB0_502:
	v_lshlrev_b32_e32 v4, 3, v136
	v_add_u32_e32 v5, 0xffffe000, v4
	s_movk_i32 s4, 0x3ff
	v_ashrrev_i32_e32 v5, 10, v5
	v_cmp_lt_i32_e32 vcc, s4, v136
	v_readlane_b32 s4, v255, 24
	v_mov_b32_e32 v57, v3
	v_cndmask_b32_e32 v5, 8, v5, vcc
	v_add_u32_e32 v5, s4, v5
	v_mul_hi_i32_i24_e32 v7, 0x12000, v5
	v_mul_i32_i24_e32 v6, 0x12000, v5
	v_lshl_add_u64 v[32:33], s[8:9], 0, v[6:7]
	s_mov_b64 s[4:5], 0x2000
	v_ashrrev_i32_e32 v5, 31, v4
	v_lshl_add_u64 v[34:35], v[32:33], 0, s[4:5]
	v_lshlrev_b64 v[4:5], 12, v[4:5]
	v_lshl_add_u64 v[4:5], v[36:37], 0, v[4:5]
	v_lshl_add_u64 v[8:9], v[34:35], 0, v[2:3]
	global_load_dwordx2 v[128:129], v[4:5], off
	global_load_dwordx2 v[126:127], v[4:5], off offset:512
	global_load_dwordx2 v[124:125], v[4:5], off offset:1024
	global_load_dwordx2 v[122:123], v[4:5], off offset:1536
	global_load_dwordx2 v[120:121], v[4:5], off offset:2048
	global_load_dwordx2 v[118:119], v[4:5], off offset:2560
	global_load_dwordx2 v[116:117], v[4:5], off offset:3072
	global_load_dwordx2 v[114:115], v[4:5], off offset:3584
	s_nop 0
	global_load_dwordx4 v[4:7], v[38:39], off
	v_lshl_add_u64 v[24:25], v[32:33], 0, v[2:3]
	global_load_dwordx4 v[8:11], v[8:9], off
	v_lshl_add_u64 v[12:13], v[34:35], 0, v[56:57]
	v_mov_b32_e32 v59, v3
	v_lshl_add_u64 v[16:17], v[34:35], 0, v[58:59]
	v_mov_b32_e32 v61, v3
	v_lshl_add_u64 v[20:21], v[34:35], 0, v[60:61]
	v_mov_b32_e32 v63, v3
	v_mov_b32_e32 v65, v3
	v_lshl_add_u64 v[28:29], v[34:35], 0, v[64:65]
	v_mov_b32_e32 v69, v3
	v_lshl_add_u64 v[110:111], v[34:35], 0, v[68:69]
	v_mov_b32_e32 v71, v3
	s_mov_b32 s14, 0
	global_load_dwordx4 v[244:247], v[24:25], off
	global_load_dwordx4 v[244:247], v[40:41], off
	global_load_dwordx4 v[244:247], v[12:13], off
	global_load_dwordx4 v[244:247], v[24:25], off offset:1024
	global_load_dwordx4 v[244:247], v[42:43], off
	global_load_dwordx4 v[244:247], v[16:17], off
	global_load_dwordx4 v[244:247], v[24:25], off offset:2048
	global_load_dwordx4 v[244:247], v[44:45], off
	global_load_dwordx4 v[244:247], v[20:21], off
	global_load_dwordx4 v[244:247], v[24:25], off offset:3072
	global_load_dwordx4 v[244:247], v[46:47], off
	v_lshl_add_u64 v[250:251], v[34:35], 0, v[62:63]
	global_load_dwordx4 v[244:247], v[250:251], off
	v_lshl_add_u64 v[250:251], v[32:33], 0, v[62:63]
	global_load_dwordx4 v[244:247], v[250:251], off
	global_load_dwordx4 v[244:247], v[48:49], off
	global_load_dwordx4 v[244:247], v[28:29], off
	v_lshl_add_u64 v[250:251], v[32:33], 0, v[64:65]
	global_load_dwordx4 v[244:247], v[250:251], off
	global_load_dwordx4 v[244:247], v[50:51], off
	global_load_dwordx4 v[244:247], v[110:111], off
	v_lshl_add_u64 v[250:251], v[32:33], 0, v[68:69]
	global_load_dwordx4 v[244:247], v[250:251], off
	global_load_dwordx4 v[244:247], v[52:53], off
	v_lshl_add_u64 v[250:251], v[34:35], 0, v[70:71]
	global_load_dwordx4 v[244:247], v[250:251], off
	v_lshl_add_u64 v[250:251], v[32:33], 0, v[70:71]
	global_load_dwordx4 v[244:247], v[250:251], off
	s_waitcnt vmcnt(0)
	v_pk_add_f32 v[10:11], v[10:11], 1.0 op_sel_hi:[1,0]
	v_pk_add_f32 v[8:9], v[8:9], 1.0 op_sel_hi:[1,0]
	v_pk_mul_f32 v[86:87], v[6:7], v[10:11]
	v_pk_mul_f32 v[88:89], v[4:5], v[8:9]
	global_load_dwordx4 v[4:7], v[24:25], off
	global_load_dwordx4 v[8:11], v[40:41], off
	s_nop 0
	global_load_dwordx4 v[12:15], v[12:13], off
	s_waitcnt vmcnt(0)
	v_pk_add_f32 v[14:15], v[14:15], 1.0 op_sel_hi:[1,0]
	v_pk_add_f32 v[12:13], v[12:13], 1.0 op_sel_hi:[1,0]
	v_pk_mul_f32 v[90:91], v[10:11], v[14:15]
	v_pk_mul_f32 v[92:93], v[8:9], v[12:13]
	global_load_dwordx4 v[8:11], v[24:25], off offset:1024
	global_load_dwordx4 v[12:15], v[42:43], off
	s_nop 0
	global_load_dwordx4 v[16:19], v[16:17], off
	s_waitcnt vmcnt(0)
	v_pk_add_f32 v[18:19], v[18:19], 1.0 op_sel_hi:[1,0]
	v_pk_add_f32 v[16:17], v[16:17], 1.0 op_sel_hi:[1,0]
	v_pk_mul_f32 v[94:95], v[14:15], v[18:19]
	v_pk_mul_f32 v[96:97], v[12:13], v[16:17]
	global_load_dwordx4 v[12:15], v[24:25], off offset:2048
	global_load_dwordx4 v[16:19], v[44:45], off
	s_nop 0
	global_load_dwordx4 v[20:23], v[20:21], off
	s_waitcnt vmcnt(0)
	v_pk_add_f32 v[22:23], v[22:23], 1.0 op_sel_hi:[1,0]
	v_pk_add_f32 v[20:21], v[20:21], 1.0 op_sel_hi:[1,0]
	v_pk_mul_f32 v[98:99], v[18:19], v[22:23]
	v_pk_mul_f32 v[100:101], v[16:17], v[20:21]
	global_load_dwordx4 v[16:19], v[24:25], off offset:3072
	global_load_dwordx4 v[20:23], v[46:47], off
	v_lshl_add_u64 v[24:25], v[34:35], 0, v[62:63]
	global_load_dwordx4 v[24:27], v[24:25], off
	v_lshl_add_u64 v[34:35], v[34:35], 0, v[70:71]
	s_waitcnt vmcnt(0)
	v_pk_add_f32 v[24:25], v[24:25], 1.0 op_sel_hi:[1,0]
	v_pk_add_f32 v[26:27], v[26:27], 1.0 op_sel_hi:[1,0]
	v_pk_mul_f32 v[104:105], v[20:21], v[24:25]
	v_lshl_add_u64 v[20:21], v[32:33], 0, v[62:63]
	v_pk_mul_f32 v[102:103], v[22:23], v[26:27]
	global_load_dwordx4 v[20:23], v[20:21], off
	s_nop 0
	global_load_dwordx4 v[24:27], v[48:49], off
	s_nop 0
	global_load_dwordx4 v[28:31], v[28:29], off
	s_waitcnt vmcnt(0)
	v_pk_add_f32 v[28:29], v[28:29], 1.0 op_sel_hi:[1,0]
	v_pk_add_f32 v[30:31], v[30:31], 1.0 op_sel_hi:[1,0]
	v_pk_mul_f32 v[108:109], v[24:25], v[28:29]
	v_lshl_add_u64 v[24:25], v[32:33], 0, v[64:65]
	v_pk_mul_f32 v[106:107], v[26:27], v[30:31]
	global_load_dwordx4 v[24:27], v[24:25], off
	s_nop 0
	global_load_dwordx4 v[28:31], v[50:51], off
	s_nop 0
	global_load_dwordx4 v[110:113], v[110:111], off
	s_waitcnt vmcnt(0)
	v_pk_add_f32 v[112:113], v[112:113], 1.0 op_sel_hi:[1,0]
	v_pk_add_f32 v[130:131], v[110:111], 1.0 op_sel_hi:[1,0]
	v_pk_mul_f32 v[110:111], v[30:31], v[112:113]
	v_pk_mul_f32 v[112:113], v[28:29], v[130:131]
	v_lshl_add_u64 v[28:29], v[32:33], 0, v[68:69]
	global_load_dwordx4 v[28:31], v[28:29], off
	s_nop 0
	global_load_dwordx4 v[132:135], v[52:53], off
	global_load_dwordx4 v[138:141], v[34:35], off
	v_lshl_add_u64 v[32:33], v[32:33], 0, v[70:71]
	s_waitcnt vmcnt(0)
	v_pk_add_f32 v[34:35], v[140:141], 1.0 op_sel_hi:[1,0]
	s_nop 0
	v_pk_mul_f32 v[130:131], v[134:135], v[34:35]
	global_load_dwordx4 v[32:35], v[32:33], off
	v_pk_add_f32 v[138:139], v[138:139], 1.0 op_sel_hi:[1,0]
	s_nop 0
	v_pk_mul_f32 v[132:133], v[132:133], v[138:139]
	s_cmp_eq_u32 s14, 7
	v_add_u32_e32 v134, s14, v137
	s_cbranch_scc1 .LBB0_505
	s_branch .LBB0_504
